# v17: v16 + second-round weight-transpose items moved to the 64 blocks without adaLN work
# speedup vs baseline: 1.0860x; 1.0066x over previous
; #define LAS __attribute__((address_space(3)))
; __global__ void __launch_bounds__(512) fwd_megakernel(Args a) {
;     ...
;     {
;         LAS float* scr = (LAS float*)(lds + wid * 16384);
;         const int gw = blk * 8 + wid, NGW = G * 8;
;         constexpr int I_IN = (DM / 64) * (NIN / 32), I_OUT = (DM / 64) * (DM / 32);
;         for (int it = gw; it < I_IN + I_OUT; it += NGW) {
;             if (it < I_IN) transpose_item<true>(a.w_in, DM, NIN, WinT, scr, it, lane);
;             else transpose_item<false>(a.w_out, DM, DM, WoutT, scr, it - I_IN, lane);
;         }
;     }
.LBB0_27:
	s_add_u32 s2, s78, 0x100000
	s_addc_u32 s3, s79, 0
	s_add_u32 s64, s78, 0x900000
	s_addc_u32 s65, s79, 0
	s_lshl_b32 s0, s61, 3
	s_add_i32 s6, s5, s0
	s_lshl_b32 s4, s62, 3
	s_cmpk_gt_i32 s6, 0x9ff
	s_cbranch_scc1 .LBB0_34
	v_lshlrev_b32_e32 v0, 5, v236
	s_lshl_b32 s0, s5, 14
	v_and_b32_e32 v14, 0x400, v0
	v_and_b32_e32 v0, 31, v236
	s_waitcnt lgkmcnt(0)
	v_lshlrev_b32_e32 v4, 3, v236
	s_add_i32 s0, s0, 0
	v_lshlrev_b32_e32 v0, 2, v0
	v_lshrrev_b32_e32 v15, 5, v133
	v_lshrrev_b32_e32 v16, 3, v133
	v_and_b32_e32 v4, 56, v4
	v_mov_b32_e32 v1, 0
	v_add_u32_e32 v10, s0, v0
	v_mul_u32_u24_e32 v11, 0x84, v15
	v_mul_u32_u24_e32 v6, 0x84, v4
	v_lshlrev_b32_e32 v7, 2, v16
	v_lshlrev_b32_e32 v8, 1, v4
	v_mov_b32_e32 v9, v1
	v_add3_u32 v17, s0, v6, v7
	s_lshl_b32 s0, s6, 1
	v_add_u32_e32 v22, v10, v11
	s_mov_b32 s1, 0
	v_lshl_add_u64 v[2:3], s[74:75], 0, v[0:1]
	v_lshl_add_u64 v[4:5], s[64:65], 0, v[8:9]
	v_or_b32_e32 v18, 8, v16
	v_or_b32_e32 v19, 16, v16
	v_or_b32_e32 v20, 24, v16
	v_lshl_add_u64 v[6:7], s[90:91], 0, v[0:1]
	v_lshl_add_u64 v[8:9], s[2:3], 0, v[8:9]
	v_or_b32_e32 v21, 0xf800, v14
	s_lshl_b32 s5, s6, 5
	s_movk_i32 s7, 0x4000
	s_lshl_b32 s12, s6, 7
	s_mov_b32 s13, 0x10000
	s_lshl_b32 s14, s6, 11
	s_mov_b32 s15, 0x100000
	s_add_i32 s16, s0, 0xfffff000
	s_movk_i32 s17, 0x400
	s_mov_b32 s18, 0xffff0000
	s_movk_i32 s19, 0x7fff
	v_add_u32_e32 v23, 0x400, v22
	v_add_u32_e32 v24, 0x800, v22
	v_add_u32_e32 v25, 0xc00, v22
	v_add_u32_e32 v26, 0x1000, v22
	v_add_u32_e32 v27, 0x1400, v22
	v_add_u32_e32 v28, 0x1800, v22
	v_add_u32_e32 v29, 0x1c00, v22
	s_mov_b32 s22, s6
	s_branch .LBB0_30
.LBB0_29:
	s_addk_i32 s22, 0x200
	s_add_i32 s5, s5, s7
	s_add_i32 s12, s12, s13
	s_add_i32 s14, s14, s15
	s_add_i32 s16, s16, s17
	s_cmpk_gt_i32 s22, 0x9ff
	s_cbranch_scc1 .LBB0_34
	s_cmpk_lt_i32 s22, 0x800
	s_cbranch_scc1 .LBB0_34
